# attention cross-unit prefetch (next unit K0/V0/K1/K2 DMA + Q rows issued at the epilogue top) and, for units>0, no wait for the previous unit's output stores before the first QK MFMA
# speedup vs baseline: 1.0327x; 1.0308x over previous
.Lxu_skip4:
	s_waitcnt vmcnt(3) lgkmcnt(0)
	s_barrier
	ds_read_b128 v[32:35], v225
	ds_read_b128 v[36:39], v225 offset:512
	s_lshl_b32 s36, s36, 2
	s_add_i32 s40, s36, 0
	s_mov_b64 s[36:37], 0x6000
	v_mov_b32_e32 v184, 0
	s_mov_b32 s41, -1
	s_movk_i32 s43, 0x2000
	s_movk_i32 s42, 0x4000
	s_mov_b64 s[48:49], 0x2000
	v_lshl_add_u32 v220, v215, 2, s40
	s_cmp_lg_u32 s28, 0
	s_cbranch_scc1 .Lxu_w0
	s_waitcnt vmcnt(0)
.Lxu_w0:
	s_waitcnt lgkmcnt(0)
	v_mov_b32_e32 v156, v228
	v_mov_b32_e32 v157, v229
	v_mov_b32_e32 v158, v230
	v_mov_b32_e32 v159, v231
	v_mov_b32_e32 v152, v232
	v_mov_b32_e32 v153, v233
	v_mov_b32_e32 v154, v234
	v_mov_b32_e32 v155, v235
	v_mov_b32_e32 v140, v236
	v_mov_b32_e32 v141, v237
	v_mov_b32_e32 v142, v238
	v_mov_b32_e32 v143, v239
	v_mov_b32_e32 v132, v240
	v_mov_b32_e32 v133, v241
	v_mov_b32_e32 v134, v242
	v_mov_b32_e32 v135, v243
	s_nop 1
	v_mfma_f32_32x32x16_bf16 v[16:31], v[32:35], v[156:159], v[0:15]
	v_mfma_f32_32x32x16_bf16 v[0:15], v[36:39], v[156:159], v[0:15]
	ds_read_b128 v[32:35], v225 offset:2048
	ds_read_b128 v[36:39], v225 offset:2560
	s_waitcnt lgkmcnt(1)
	v_mfma_f32_32x32x16_bf16 v[16:31], v[32:35], v[152:155], v[16:31]
	s_waitcnt lgkmcnt(0)
	v_mfma_f32_32x32x16_bf16 v[0:15], v[36:39], v[152:155], v[0:15]
	ds_read_b128 v[32:35], v225 offset:4096
	ds_read_b128 v[36:39], v225 offset:4608
	s_waitcnt lgkmcnt(1)
	v_mfma_f32_32x32x16_bf16 v[16:31], v[32:35], v[140:143], v[16:31]
	ds_read_b128 v[32:35], v225 offset:6144
	s_waitcnt lgkmcnt(1)
	v_mfma_f32_32x32x16_bf16 v[0:15], v[36:39], v[140:143], v[0:15]
	ds_read_b128 v[36:39], v225 offset:6656
	s_waitcnt lgkmcnt(1)
	v_mfma_f32_32x32x16_bf16 v[16:31], v[32:35], v[132:135], v[16:31]
	v_lshlrev_b32_e32 v32, 1, v84
	v_lshlrev_b32_e32 v33, 4, v84
	v_and_b32_e32 v218, 32, v32
	v_and_b32_e32 v32, 0xc0, v33
	v_lshl_or_b32 v219, v216, 8, v32
	v_add_u32_e32 v80, 0, v218
	v_add3_u32 v224, v80, v217, v219
	s_waitcnt lgkmcnt(0)
	v_mfma_f32_32x32x16_bf16 v[0:15], v[36:39], v[132:135], v[0:15]
	s_nop 15
	s_nop 7
	s_nop 0
	v_max3_f32 v32, v16, v17, v0
	v_max3_f32 v33, v18, v19, v1
	s_nop 0
	v_max3_f32 v32, v32, v2, v3
	v_max3_f32 v33, v33, v22, v23
	s_nop 0
	v_max3_f32 v32, v32, v20, v21
	v_max3_f32 v33, v33, v6, v7
	s_nop 0
	v_max3_f32 v32, v32, v4, v5
	v_max3_f32 v33, v33, v26, v27
	s_nop 0
	v_max3_f32 v32, v32, v24, v25
	v_max3_f32 v33, v33, v10, v11
	s_nop 0
	v_max3_f32 v32, v32, v8, v9
	v_max3_f32 v33, v33, v30, v31
	s_nop 0
	v_max3_f32 v32, v32, v28, v29
	v_max3_f32 v33, v33, v14, v15
	s_nop 0
	v_max3_f32 v32, v32, v12, v13
	s_nop 0
	v_max_f32_e32 v32, v32, v33
	s_nop 0
	v_mov_b32_e32 v33, v32
	s_nop 1
	v_permlane32_swap_b32_e32 v32, v33
	v_max_f32_e32 v32, v32, v33
	s_nop 0
	v_add_f32_e32 v221, v189, v32
	v_sub_f32_e32 v16, v16, v32
	v_sub_f32_e32 v0, v0, v32
	v_sub_f32_e32 v17, v17, v32
	v_sub_f32_e32 v1, v1, v32
	v_sub_f32_e32 v18, v18, v32
	v_sub_f32_e32 v2, v2, v32
	v_sub_f32_e32 v19, v19, v32
	v_sub_f32_e32 v3, v3, v32
	v_sub_f32_e32 v20, v20, v32
	v_sub_f32_e32 v4, v4, v32
	v_sub_f32_e32 v21, v21, v32
	v_sub_f32_e32 v5, v5, v32
	v_sub_f32_e32 v22, v22, v32
	v_sub_f32_e32 v6, v6, v32
	v_sub_f32_e32 v23, v23, v32
	v_sub_f32_e32 v7, v7, v32
	v_sub_f32_e32 v24, v24, v32
	v_sub_f32_e32 v8, v8, v32
	v_sub_f32_e32 v25, v25, v32
	v_sub_f32_e32 v9, v9, v32
	v_sub_f32_e32 v26, v26, v32
	v_sub_f32_e32 v10, v10, v32
	v_sub_f32_e32 v27, v27, v32
	v_sub_f32_e32 v11, v11, v32
	v_sub_f32_e32 v28, v28, v32
	v_sub_f32_e32 v12, v12, v32
	v_sub_f32_e32 v29, v29, v32
	v_sub_f32_e32 v13, v13, v32
	v_sub_f32_e32 v30, v30, v32
	v_sub_f32_e32 v14, v14, v32
	v_sub_f32_e32 v31, v31, v32
	v_sub_f32_e32 v15, v15, v32
	s_nop 0
	v_xor_b32_e32 v32, 0x80000000, v221
	v_mov_b32_e32 v33, v32
	v_mov_b32_e32 v34, v32
	v_mov_b32_e32 v35, v32
	v_mov_b32_e32 v36, v32
	v_mov_b32_e32 v37, v32
	v_mov_b32_e32 v38, v32
	v_mov_b32_e32 v39, v32
	v_mov_b32_e32 v40, v32
	v_mov_b32_e32 v41, v32
	v_mov_b32_e32 v42, v32
	v_mov_b32_e32 v43, v32
	v_mov_b32_e32 v44, v32
	v_mov_b32_e32 v45, v32
	v_mov_b32_e32 v46, v32
	v_mov_b32_e32 v47, v32
	s_waitcnt vmcnt(0) lgkmcnt(0)
	s_barrier
	v_exp_f32_e32 v48, v0
	v_exp_f32_e32 v49, v1
	v_lshl_add_u64 v[0:1], v[204:205], 0, s[36:37]
	s_mov_b32 s36, m0
	s_mov_b32 m0, s39
	s_nop 0
	global_load_lds_dwordx4 v[0:1], off
	s_mov_b32 m0, s36
	v_lshl_add_u64 v[0:1], v[202:203], 0, s[8:9]
	s_add_i32 s36, s39, 0x8000
	s_mov_b32 s37, m0
	s_mov_b32 m0, s36
	s_nop 0
	global_load_lds_dwordx4 v[0:1], off
	s_mov_b32 m0, s37
	ds_read_b128 v[80:83], v225 offset:8192
	ds_read_b128 v[164:167], v225 offset:8704
	ds_read_b128 v[168:171], v225 offset:10240
	ds_read_b128 v[160:163], v225 offset:10752
	ds_read_b128 v[124:127], v225 offset:12288
	ds_read_b128 v[120:123], v225 offset:12800
	ds_read_b128 v[116:119], v225 offset:14336
	ds_read_b128 v[112:115], v225 offset:14848
	v_readlane_b32 s8, v253, 53
	s_add_u32 s20, s8, s20
	v_readlane_b32 s8, v253, 54
	s_addc_u32 s21, s8, s21
	v_exp_f32_e32 v64, v16
	v_exp_f32_e32 v65, v17
	v_exp_f32_e32 v66, v18
	v_exp_f32_e32 v67, v19
	v_exp_f32_e32 v68, v20
	v_exp_f32_e32 v69, v21
	v_exp_f32_e32 v70, v22
	v_exp_f32_e32 v71, v23
	v_exp_f32_e32 v72, v24
	v_exp_f32_e32 v73, v25
	v_exp_f32_e32 v74, v26
	v_exp_f32_e32 v75, v27
	v_exp_f32_e32 v76, v28
	v_exp_f32_e32 v77, v29
	v_exp_f32_e32 v78, v30
	v_exp_f32_e32 v79, v31
	v_exp_f32_e32 v50, v2
	v_exp_f32_e32 v51, v3
	v_exp_f32_e32 v52, v4
	v_exp_f32_e32 v53, v5
	v_exp_f32_e32 v54, v6
	v_exp_f32_e32 v55, v7
	v_exp_f32_e32 v56, v8
	v_exp_f32_e32 v57, v9
	v_exp_f32_e32 v58, v10
	v_exp_f32_e32 v59, v11
	v_exp_f32_e32 v60, v12
	v_exp_f32_e32 v61, v13
	v_exp_f32_e32 v62, v14
	v_exp_f32_e32 v63, v15
	v_lshl_add_u64 v[180:181], s[20:21], 0, v[188:189]
	v_and_b32_e32 v0, 3, v84
	s_and_b32 s20, s38, 0xc00
	s_waitcnt vmcnt(2) lgkmcnt(0)
	s_barrier
	v_lshlrev_b32_e32 v0, 4, v0
	v_lshl_or_b32 v1, v85, 6, s20
	v_readlane_b32 s8, v253, 55
	v_or3_b32 v0, s30, v0, v1
	v_mov_b32_e32 v1, s31
	v_readlane_b32 s9, v253, 56
	v_cmp_gt_u32_e64 s[36:37], 32, v222
	s_mov_b32 s20, 0
	v_lshl_add_u64 v[182:183], s[8:9], 0, v[0:1]
	s_movk_i32 s9, 0x60
	v_mov_b32_e32 v0, 0
	v_mov_b32_e32 v1, v184
	v_mov_b32_e32 v2, v184
	v_mov_b32_e32 v3, v184
	v_mov_b32_e32 v4, v184
	v_mov_b32_e32 v5, v184
	v_mov_b32_e32 v6, v184
	v_mov_b32_e32 v7, v184
	v_mov_b32_e32 v8, v184
	v_mov_b32_e32 v9, v184
	v_mov_b32_e32 v10, v184
	v_mov_b32_e32 v11, v184
	v_mov_b32_e32 v12, v184
	v_mov_b32_e32 v13, v184
	v_mov_b32_e32 v14, v184
	v_mov_b32_e32 v15, v184
	v_mov_b32_e32 v16, 0
	v_mov_b32_e32 v17, v184
	v_mov_b32_e32 v18, v184
	v_mov_b32_e32 v19, v184
	v_mov_b32_e32 v20, v184
	v_mov_b32_e32 v21, v184
	v_mov_b32_e32 v22, v184
	v_mov_b32_e32 v23, v184
	v_mov_b32_e32 v24, v184
	v_mov_b32_e32 v25, v184
	v_mov_b32_e32 v26, v184
	v_mov_b32_e32 v27, v184
	v_mov_b32_e32 v28, v184
	v_mov_b32_e32 v29, v184
	v_mov_b32_e32 v30, v184
	v_mov_b32_e32 v31, v184
	s_cmp_lg_u32 s101, 0
	s_cbranch_scc1 .Lattn_fast_top
